# P4 queue item order table: longest-first (attention q-blocks, sample attention, S5 output items, short items last)
# speedup vs baseline: 1.0108x; 1.0108x over previous
; __global__ void __launch_bounds__(512, 2) fwd_kernel(Args A0) {
;     ...
;           static constexpr unsigned char ORD[108] = {60, 61, 62, 63, 56, 57, 58, 59, 52, 53, 54, 55, 48, 49, 50, 51, 44, 45, 46, 47, 40, 41, 42, 43, 36, 37, 38, 39, 32, 33, 34, 35, 28, 29, 30, 31, 64, 65, 66, 67, 68, 69, 70, 71, 72, 73, 74, 75, 24, 76, 77, 25, 78, 79, 26, 80, 81, 27, 82, 83, 20, 84, 85, 21, 86, 87, 22, 88, 89, 23, 90, 91, 16, 92, 93, 17, 94, 95, 18, 96, 97, 19, 98, 99, 12, 100, 101, 13, 102, 103, 14, 104, 105, 15, 106, 107, 8, 9, 10, 11, 4, 5, 6, 7, 0, 1, 2, 3};
_ZZ10fwd_kernel4ArgsE3ORD.const:
	.ascii	"\074\075\076\077\070\071\072\073\064\065\066\067\060\061\062\063\054\055\056\057\050\051\052\053\044\045\046\047\040\041\042\043\034\035\036\037\030\031\032\033\100\101\102\103\104\105\106\107\024\025\026\027\020\021\022\023\014\015\016\017\010\011\012\013\114\115\116\117\120\121\122\123\124\125\126\127\130\131\132\133\004\005\006\007\134\135\136\137\140\141\142\143\144\145\146\147\150\151\152\153\000\001\002\003\110\111\112\113"
	.size	_ZZ10fwd_kernel4ArgsE3ORD.const, 108

; __global__ void __launch_bounds__(512, 2) fwd_kernel(Args A0) {
;     ...
;           static constexpr unsigned char ORD[108] = {60, 61, 62, 63, 56, 57, 58, 59, 52, 53, 54, 55, 48, 49, 50, 51, 44, 45, 46, 47, 40, 41, 42, 43, 36, 37, 38, 39, 32, 33, 34, 35, 28, 29, 30, 31, 64, 65, 66, 67, 68, 69, 70, 71, 72, 73, 74, 75, 24, 76, 77, 25, 78, 79, 26, 80, 81, 27, 82, 83, 20, 84, 85, 21, 86, 87, 22, 88, 89, 23, 90, 91, 16, 92, 93, 17, 94, 95, 18, 96, 97, 19, 98, 99, 12, 100, 101, 13, 102, 103, 14, 104, 105, 15, 106, 107, 8, 9, 10, 11, 4, 5, 6, 7, 0, 1, 2, 3};
	.type	__hip_cuid_af2ee39715b257f4,@object
